# baseline (speedup 1.0000x reference)
.LBB0_389:
	s_cmp_gt_u32 s87, 29
	s_cbranch_scc1 .Ltail_c0
	s_add_i32 s3, s86, 0x8000
	s_and_b32 s3, s3, 0xc000
	s_add_u32 s0, s84, s56
	s_addc_u32 s1, s85, s57
	s_add_u32 s10, s0, s40
	s_addc_u32 s11, s1, s41
	s_add_u32 s0, s0, s18
	s_addc_u32 s1, s1, s19
	s_add_i32 m0, s81, s3
	s_nop 0
	global_load_lds_dwordx4 v250, s[0:1]
	s_add_i32 m0, s80, s3
	s_add_i32 s3, s3, 0x2000
	global_load_lds_dwordx4 v251, s[10:11]
	s_add_u32 s0, s0, 0xb8000
	s_addc_u32 s1, s1, 0
	s_add_i32 m0, s81, s3
	s_add_u32 s10, s10, 0xb8000
	s_addc_u32 s11, s11, 0
	global_load_lds_dwordx4 v250, s[0:1]
	s_add_i32 m0, s80, s3
	s_nop 0
	global_load_lds_dwordx4 v251, s[10:11]
	s_waitcnt vmcnt(8)

.Ltail_c0:
	s_cmp_gt_u32 s87, 30
	s_cbranch_scc1 .Lv0_c0
	s_waitcnt vmcnt(4)
	s_branch .Lbar_c0

.LBB0_1243:
	s_cmpk_gt_u32 s79, 0xfd
	s_cbranch_scc1 .Ltail_c1
	s_add_i32 s3, s77, 0x8000
	s_and_b32 s3, s3, 0xc000
	s_add_u32 s0, s69, s86
	s_addc_u32 s1, s76, s87
	s_add_u32 s10, s0, s36
	s_addc_u32 s11, s1, s37
	s_add_u32 s0, s0, s16
	s_addc_u32 s1, s1, s17
	s_add_i32 m0, s68, s3
	s_nop 0
	global_load_lds_dwordx4 v250, s[0:1]
	s_add_i32 m0, s57, s3
	s_add_i32 s3, s3, 0x2000
	global_load_lds_dwordx4 v251, s[10:11]
	s_add_u32 s0, s0, 0xb8000
	s_addc_u32 s1, s1, 0
	s_add_i32 m0, s68, s3
	s_add_u32 s10, s10, 0xb8000
	s_addc_u32 s11, s11, 0
	global_load_lds_dwordx4 v250, s[0:1]
	s_add_i32 m0, s57, s3
	s_nop 0
	global_load_lds_dwordx4 v251, s[10:11]
	s_waitcnt vmcnt(8)

.Ltail_c1:
	s_cmpk_gt_u32 s79, 0xfe
	s_cbranch_scc1 .Lv0_c1
	s_waitcnt vmcnt(4)
	s_branch .Lbar_c1

.LBB0_2097:
	s_cmpk_gt_u32 s69, 0xfd
	s_cbranch_scc1 .Ltail_c2
	s_add_i32 s3, s68, 0x8000
	s_and_b32 s3, s3, 0xc000
	s_add_u32 s0, s66, s58
	s_addc_u32 s1, s67, s59
	s_add_u32 s6, s0, s16
	s_addc_u32 s7, s1, s17
	s_add_u32 s0, s0, s14
	s_addc_u32 s1, s1, s15
	s_add_i32 m0, s65, s3
	s_nop 0
	global_load_lds_dwordx4 v250, s[0:1]
	s_add_i32 m0, s64, s3
	s_add_i32 s3, s3, 0x2000
	global_load_lds_dwordx4 v251, s[6:7]
	s_add_u32 s0, s0, 0xb8000
	s_addc_u32 s1, s1, 0
	s_add_i32 m0, s65, s3
	s_add_u32 s6, s6, 0xb8000
	s_addc_u32 s7, s7, 0
	global_load_lds_dwordx4 v250, s[0:1]
	s_add_i32 m0, s64, s3
	s_nop 0
	global_load_lds_dwordx4 v251, s[6:7]
	s_waitcnt vmcnt(8)

.Ltail_c2:
	s_cmpk_gt_u32 s69, 0xfe
	s_cbranch_scc1 .Lv0_c2
	s_waitcnt vmcnt(4)
	s_branch .Lbar_c2
